# NA attention first in-loop QK^T block: single K-fragment buffer (ds_read, wait 0, MFMA x12) replaced by two alternating buffers using dead v248-251
# baseline (speedup 1.0000x reference)
.LBB0_451:
	v_cndmask_b32_e64 v228, v96, v194, s[16:17]
	v_mul_f32_e32 v196, 0xbe0293ee, v228
	v_mov_b32_e32 v197, v196
	v_pk_fma_f32 v[94:95], v[94:95], s[36:37], v[196:197] op_sel_hi:[1,0,0]
	v_pk_fma_f32 v[92:93], v[92:93], s[36:37], v[196:197] op_sel_hi:[1,0,0]
	v_pk_fma_f32 v[90:91], v[90:91], s[36:37], v[196:197] op_sel_hi:[1,0,0]
	v_pk_fma_f32 v[88:89], v[88:89], s[36:37], v[196:197] op_sel_hi:[1,0,0]
	v_pk_fma_f32 v[86:87], v[86:87], s[36:37], v[196:197] op_sel_hi:[1,0,0]
	v_pk_fma_f32 v[84:85], v[84:85], s[36:37], v[196:197] op_sel_hi:[1,0,0]
	v_pk_fma_f32 v[82:83], v[82:83], s[36:37], v[196:197] op_sel_hi:[1,0,0]
	v_pk_fma_f32 v[80:81], v[80:81], s[36:37], v[196:197] op_sel_hi:[1,0,0]
	v_exp_f32_e32 v192, v82
	v_exp_f32_e32 v194, v80
	v_exp_f32_e32 v195, v81
	v_exp_f32_e32 v193, v83
	v_exp_f32_e32 v190, v84
	v_exp_f32_e32 v191, v85
	v_exp_f32_e32 v188, v86
	v_exp_f32_e32 v189, v87
	v_exp_f32_e32 v186, v88
	v_exp_f32_e32 v187, v89
	v_exp_f32_e32 v184, v90
	v_exp_f32_e32 v185, v91
	v_exp_f32_e32 v182, v92
	v_exp_f32_e32 v183, v93
	v_exp_f32_e32 v174, v94
	v_exp_f32_e32 v175, v95
	s_mov_b32 s29, 0x42b504f3
	s_waitcnt lgkmcnt(0)
	s_barrier
	ds_read_b128 v[80:83], v208 offset:32768
	ds_read_b128 v[198:201], v213 offset:32768
	s_cmp_lt_u32 s37, 3
	s_waitcnt lgkmcnt(1)
	v_mfma_f32_32x32x16_bf16 v[96:111], v[80:83], v[120:123], 0
	ds_read_b128 v[80:83], v208 offset:40960
	s_waitcnt lgkmcnt(1)
	v_mfma_f32_32x32x16_bf16 v[96:111], v[198:201], v[112:115], v[96:111]
	ds_read_b128 v[198:201], v213 offset:40960
	ds_read_b128 v[248:251], v214 offset:32768
	s_waitcnt lgkmcnt(2)
	v_mfma_f32_32x32x16_bf16 v[80:95], v[80:83], v[120:123], 0
	s_waitcnt lgkmcnt(1)
	v_mfma_f32_32x32x16_bf16 v[80:95], v[198:201], v[112:115], v[80:95]
	ds_read_b128 v[198:201], v214 offset:40960
	s_waitcnt lgkmcnt(1)
	v_mfma_f32_32x32x16_bf16 v[96:111], v[248:251], v[132:135], v[96:111]
	ds_read_b128 v[248:251], v215 offset:32768
	s_waitcnt lgkmcnt(1)
	v_mfma_f32_32x32x16_bf16 v[80:95], v[198:201], v[132:135], v[80:95]
	ds_read_b128 v[198:201], v215 offset:40960
	s_waitcnt lgkmcnt(1)
	v_mfma_f32_32x32x16_bf16 v[96:111], v[248:251], v[140:143], v[96:111]
	ds_read_b128 v[248:251], v216 offset:32768
	s_waitcnt lgkmcnt(1)
	v_mfma_f32_32x32x16_bf16 v[80:95], v[198:201], v[140:143], v[80:95]
	ds_read_b128 v[198:201], v216 offset:40960
	s_waitcnt lgkmcnt(1)
	v_mfma_f32_32x32x16_bf16 v[96:111], v[248:251], v[136:139], v[96:111]
	ds_read_b128 v[248:251], v217 offset:32768
	s_waitcnt lgkmcnt(1)
	v_mfma_f32_32x32x16_bf16 v[80:95], v[198:201], v[136:139], v[80:95]
	ds_read_b128 v[198:201], v217 offset:40960
	s_waitcnt lgkmcnt(1)
	v_mfma_f32_32x32x16_bf16 v[96:111], v[248:251], v[128:131], v[96:111]
	ds_read_b128 v[248:251], v218 offset:32768
	s_waitcnt lgkmcnt(1)
	v_mfma_f32_32x32x16_bf16 v[80:95], v[198:201], v[128:131], v[80:95]
	ds_read_b128 v[198:201], v218 offset:40960
	s_waitcnt lgkmcnt(1)
	v_mfma_f32_32x32x16_bf16 v[96:111], v[248:251], v[124:127], v[96:111]
	ds_read_b128 v[248:251], v219 offset:32768
	s_waitcnt lgkmcnt(1)
	v_mfma_f32_32x32x16_bf16 v[80:95], v[198:201], v[124:127], v[80:95]
	ds_read_b128 v[198:201], v219 offset:40960
	s_waitcnt lgkmcnt(1)
	v_mfma_f32_32x32x16_bf16 v[96:111], v[248:251], v[116:119], v[96:111]
	s_waitcnt lgkmcnt(0)
	v_mfma_f32_32x32x16_bf16 v[80:95], v[198:201], v[116:119], v[80:95]
	s_cbranch_scc1 .LBB0_519
	s_add_i32 s1, s33, s39
	s_add_i32 s1, s1, -6
	v_cmp_ge_i32_e32 vcc, s1, v223
	v_cmp_lt_i32_e64 s[16:17], s1, v224
	s_and_b64 s[34:35], vcc, s[16:17]
	v_mov_b32_e32 v180, 0xf149f2ca
	v_mov_b32_e32 v198, 0xf149f2ca
	v_mov_b32_e32 v205, 0xf149f2ca
	v_mov_b32_e32 v178, 0xf149f2ca
	v_mov_b32_e32 v201, 0xf149f2ca
	v_mov_b32_e32 v181, 0xf149f2ca
	v_mov_b32_e32 v199, 0xf149f2ca
	v_mov_b32_e32 v200, 0xf149f2ca
	v_mov_b32_e32 v250, 0xf149f2ca
	v_mov_b32_e32 v251, 0xf149f2ca
	v_mov_b32_e32 v248, 0xf149f2ca
	v_mov_b32_e32 v249, 0xf149f2ca
	v_mov_b32_e32 v246, 0xf149f2ca
	v_mov_b32_e32 v247, 0xf149f2ca
	v_mov_b32_e32 v244, 0xf149f2ca
	v_mov_b32_e32 v245, 0xf149f2ca
	v_mov_b32_e32 v242, 0xf149f2ca
	v_mov_b32_e32 v243, 0xf149f2ca
	v_mov_b32_e32 v240, 0xf149f2ca
	v_mov_b32_e32 v241, 0xf149f2ca
	v_mov_b32_e32 v238, 0xf149f2ca
	v_mov_b32_e32 v239, 0xf149f2ca
	v_mov_b32_e32 v236, 0xf149f2ca
	v_mov_b32_e32 v237, 0xf149f2ca
	v_mov_b32_e32 v234, 0xf149f2ca
	v_mov_b32_e32 v235, 0xf149f2ca
	v_mov_b32_e32 v232, 0xf149f2ca
	v_mov_b32_e32 v233, 0xf149f2ca
	v_mov_b32_e32 v230, 0xf149f2ca
	v_mov_b32_e32 v231, 0xf149f2ca
	v_mov_b32_e32 v176, 0xf149f2ca
	v_mov_b32_e32 v229, 0xf149f2ca
	s_and_saveexec_b64 s[16:17], s[34:35]
	s_cbranch_execz .LBB0_518
	v_mov_b32_e32 v176, 0xf149f2ca
	v_mov_b32_e32 v229, 0xf149f2ca
	s_and_saveexec_b64 vcc, s[96:97]
	s_cbranch_execz .LBB0_455
	ds_read_b32 v178, v226 offset:124
	s_waitcnt lgkmcnt(0)
	v_add_f32_e32 v229, v96, v178
